# mix_c: dft_sum chunks reassigned away from the 64 half-blocks that run two retention items (same work, balanced)
# baseline (speedup 1.0000x reference)
.LBB0_202:
	s_and_b64 s[0:1], s[0:1], exec
	s_movk_i32 s0, 0x900
	s_cselect_b32 s20, 0x800, s0
	s_cselect_b32 vcc_lo, 0, 64
	v_readfirstlane_b32 s0, v193
	s_lshr_b32 s0, s0, 8
	v_readlane_b32 s1, v254, 11
	s_add_i32 s30, s0, s1
	s_sub_i32 s30, s30, vcc_lo
	s_cmp_lt_i32 s30, 0
	s_cbranch_scc1 .LBB0_221
	s_cmp_ge_i32 s30, s20
	s_cbranch_scc1 .LBB0_221
	v_readlane_b32 s4, v254, 0
	v_readlane_b32 s5, v254, 1
	s_load_dword s1, s[4:5], 0x0
	s_lshl_b32 s26, s30, 2
	s_waitcnt lgkmcnt(0)
	s_lshl_b32 s27, s1, 1
	s_sub_i32 s27, s27, vcc_lo
	s_lshl_b32 s33, s27, 3
	s_branch .LBB0_207
